# gemm_small (sample rows of the gate / out / down projections): every fragment load of a task is issued up front with counted vmcnt waits instead of a two-buffer rolling wait
# speedup vs baseline: 1.0034x; 1.0034x over previous
; DI unsigned pk2(float a, float b) { f32x2 f = {a, b}; bf2_t r = __builtin_convertvector(f, bf2_t); return __builtin_bit_cast(unsigned, r); }
; DI float bf_lo(unsigned u) { return __uint_as_float(u << 16); }
; DI float bf_hi(unsigned u) { return __uint_as_float(u & 0xffff0000u); }
; DI float sigmoidf_(float x) { return __builtin_amdgcn_rcpf(1.0f + __builtin_amdgcn_exp2f(-1.4426950408889634f * x)); }
; #define MFMA32(a, b, c) __builtin_amdgcn_mfma_f32_32x32x16_bf16((a), (b), (c), 0, 0, 0)
; template <int KIND, int KSTEPS  >
; DI void gemm_small(KP P, const bf16_t* A, int lda, const bf16_t* Bt, int ldb, int N, bf16_t* C, int ldc, char* lds) {
;     ...
;             for (int s0 = 0; s0 < KSTEPS; s0 += UN) {
;                 bf16x8 af[UN], bf[UN];
; #pragma unroll
;                 for (int s = 0; s < UN; ++s) { af[s] = *(const bf16x8*)(ap + (s0 + s) * 16); bf[s] = *(const bf16x8*)(bp + (s0 + s) * 16); }
; #pragma unroll
;                 for (int s = 0; s < UN; ++s) acc = MFMA32(bf[s], af[s], acc);
;             }
;             float* pp = part + ((pass * 8 + w) * 32 + r) * 32 + 4 * hh;
; #pragma unroll
;             for (int g = 0; g < 4; ++g) *(f32x4*)(pp + 8 * g) = (f32x4){acc[4 * g], acc[4 * g + 1], acc[4 * g + 2], acc[4 * g + 3]};
;         }
;         __syncthreads();
;         {
;             const int e = tid * 2, rr = e >> 5, cc = e & 31;
;             f32x2 s1 = {0.f, 0.f}, s2 = {0.f, 0.f};
; #pragma unroll
;             for (int ww = 0; ww < 8; ++ww) { s1 += *(const f32x2*)(part + (ww * 32 + rr) * 32 + cc); if (KIND == 2) s2 += *(const f32x2*)(part + ((8 + ww) * 32 + rr) * 32 + cc); }
;             const long row = row0 + rr; const int col = col0 + cc;
;             if (KIND == 1) { s1[0] = sigmoidf_(s1[0]); s1[1] = sigmoidf_(s1[1]); }
;             if (KIND == 2) { const unsigned ga = *(const unsigned*)(P->gates + row * 2048 + col), gb = *(const unsigned*)(P->gates + row * 2048 + 1024 + col);
;                 s1[0] = s1[0] * bf_lo(ga) + s2[0] * bf_lo(gb); s1[1] = s1[1] * bf_hi(ga) + s2[1] * bf_hi(gb); }
;             *(unsigned*)(C + row * ldc + col) = pk2(s1[0], s1[1]);
;         }
;         __syncthreads();
.LBB0_1068:
	v_lshl_add_u64 v[46:47], v[22:23], 0, v[16:17]
	v_lshl_add_u64 v[44:45], v[24:25], 0, v[16:17]
	global_load_dwordx4 v[32:35], v[46:47], off
	global_load_dwordx4 v[124:127], v[44:45], off
	global_load_dwordx4 v[36:39], v[46:47], off offset:32
	global_load_dwordx4 v[128:131], v[44:45], off offset:32
	global_load_dwordx4 v[40:43], v[46:47], off offset:64
	global_load_dwordx4 v[132:135], v[44:45], off offset:64
	global_load_dwordx4 v[48:51], v[46:47], off offset:96
	global_load_dwordx4 v[136:139], v[44:45], off offset:96
	global_load_dwordx4 v[52:55], v[46:47], off offset:128
	global_load_dwordx4 v[142:145], v[44:45], off offset:128
	global_load_dwordx4 v[56:59], v[46:47], off offset:160
	global_load_dwordx4 v[146:149], v[44:45], off offset:160
	global_load_dwordx4 v[60:63], v[46:47], off offset:192
	global_load_dwordx4 v[150:153], v[44:45], off offset:192
	global_load_dwordx4 v[64:67], v[46:47], off offset:224
	global_load_dwordx4 v[154:157], v[44:45], off offset:224
	global_load_dwordx4 v[68:71], v[46:47], off offset:256
	global_load_dwordx4 v[158:161], v[44:45], off offset:256
	global_load_dwordx4 v[72:75], v[46:47], off offset:288
	global_load_dwordx4 v[162:165], v[44:45], off offset:288
	global_load_dwordx4 v[76:79], v[46:47], off offset:320
	global_load_dwordx4 v[166:169], v[44:45], off offset:320
	global_load_dwordx4 v[80:83], v[46:47], off offset:352
	global_load_dwordx4 v[170:173], v[44:45], off offset:352
	global_load_dwordx4 v[84:87], v[46:47], off offset:384
	global_load_dwordx4 v[202:205], v[44:45], off offset:384
	global_load_dwordx4 v[88:91], v[46:47], off offset:416
	global_load_dwordx4 v[206:209], v[44:45], off offset:416
	global_load_dwordx4 v[92:95], v[46:47], off offset:448
	global_load_dwordx4 v[210:213], v[44:45], off offset:448
	global_load_dwordx4 v[96:99], v[46:47], off offset:480
	global_load_dwordx4 v[214:217], v[44:45], off offset:480
	global_load_dwordx4 v[100:103], v[46:47], off offset:512
	global_load_dwordx4 v[218:221], v[44:45], off offset:512
	global_load_dwordx4 v[104:107], v[46:47], off offset:544
	global_load_dwordx4 v[222:225], v[44:45], off offset:544
	global_load_dwordx4 v[108:111], v[46:47], off offset:576
	global_load_dwordx4 v[226:229], v[44:45], off offset:576
	global_load_dwordx4 v[112:115], v[46:47], off offset:608
	global_load_dwordx4 v[230:233], v[44:45], off offset:608
	global_load_dwordx4 v[116:119], v[46:47], off offset:640
	global_load_dwordx4 v[234:237], v[44:45], off offset:640
	global_load_dwordx4 v[120:123], v[46:47], off offset:672
	global_load_dwordx4 v[238:241], v[44:45], off offset:672
	s_waitcnt vmcnt(42)
	v_mfma_f32_32x32x16_bf16 v[0:15], v[32:35], v[124:127], v[0:15]
	s_waitcnt vmcnt(40)
	v_mfma_f32_32x32x16_bf16 v[0:15], v[36:39], v[128:131], v[0:15]
	s_waitcnt vmcnt(38)
	v_mfma_f32_32x32x16_bf16 v[0:15], v[40:43], v[132:135], v[0:15]
	s_waitcnt vmcnt(36)
	v_mfma_f32_32x32x16_bf16 v[0:15], v[48:51], v[136:139], v[0:15]
	s_waitcnt vmcnt(34)
	v_mfma_f32_32x32x16_bf16 v[0:15], v[52:55], v[142:145], v[0:15]
	s_waitcnt vmcnt(32)
	v_mfma_f32_32x32x16_bf16 v[0:15], v[56:59], v[146:149], v[0:15]
	s_waitcnt vmcnt(30)
	v_mfma_f32_32x32x16_bf16 v[0:15], v[60:63], v[150:153], v[0:15]
	s_waitcnt vmcnt(28)
	v_mfma_f32_32x32x16_bf16 v[0:15], v[64:67], v[154:157], v[0:15]
	s_waitcnt vmcnt(26)
	v_mfma_f32_32x32x16_bf16 v[0:15], v[68:71], v[158:161], v[0:15]
	s_waitcnt vmcnt(24)
	v_mfma_f32_32x32x16_bf16 v[0:15], v[72:75], v[162:165], v[0:15]
	s_waitcnt vmcnt(22)
	v_mfma_f32_32x32x16_bf16 v[0:15], v[76:79], v[166:169], v[0:15]
	s_waitcnt vmcnt(20)
	v_mfma_f32_32x32x16_bf16 v[0:15], v[80:83], v[170:173], v[0:15]
	s_waitcnt vmcnt(18)
	v_mfma_f32_32x32x16_bf16 v[0:15], v[84:87], v[202:205], v[0:15]
	s_waitcnt vmcnt(16)
	v_mfma_f32_32x32x16_bf16 v[0:15], v[88:91], v[206:209], v[0:15]
	s_waitcnt vmcnt(14)
	v_mfma_f32_32x32x16_bf16 v[0:15], v[92:95], v[210:213], v[0:15]
	s_waitcnt vmcnt(12)
	v_mfma_f32_32x32x16_bf16 v[0:15], v[96:99], v[214:217], v[0:15]
	s_waitcnt vmcnt(10)
	v_mfma_f32_32x32x16_bf16 v[0:15], v[100:103], v[218:221], v[0:15]
	s_waitcnt vmcnt(8)
	v_mfma_f32_32x32x16_bf16 v[0:15], v[104:107], v[222:225], v[0:15]
	s_waitcnt vmcnt(6)
	v_mfma_f32_32x32x16_bf16 v[0:15], v[108:111], v[226:229], v[0:15]
	s_waitcnt vmcnt(4)
	v_mfma_f32_32x32x16_bf16 v[0:15], v[112:115], v[230:233], v[0:15]
	s_waitcnt vmcnt(2)
	v_mfma_f32_32x32x16_bf16 v[0:15], v[116:119], v[234:237], v[0:15]
	s_waitcnt vmcnt(0)
	v_mfma_f32_32x32x16_bf16 v[0:15], v[120:123], v[238:241], v[0:15]
	s_nop 10
	ds_write_b128 v30, v[0:3]
	ds_write_b128 v30, v[4:7] offset:32
	ds_write_b128 v30, v[8:11] offset:64
	ds_write_b128 v30, v[12:15] offset:96
	s_waitcnt lgkmcnt(0)
	s_barrier
	ds_read2st64_b64 v[0:3], v29 offset1:8
	ds_read2st64_b64 v[4:7], v29 offset0:16 offset1:24
	ds_read2st64_b64 v[8:11], v29 offset0:32 offset1:40
	s_and_b32 s13, s8, 7
	s_and_b32 s12, s12, 0x7fffff8
	s_waitcnt lgkmcnt(2)
	v_pk_add_f32 v[0:1], v[0:1], 0 op_sel_hi:[1,0]
	s_or_b32 s12, s12, s13
	v_pk_add_f32 v[12:13], v[0:1], v[2:3]
	ds_read2st64_b64 v[0:3], v29 offset0:48 offset1:56
	s_waitcnt lgkmcnt(2)
	v_pk_add_f32 v[4:5], v[12:13], v[4:5]
	s_add_i32 s8, s8, s6
	v_pk_add_f32 v[4:5], v[4:5], v[6:7]
	s_add_i32 s7, s7, s6
	s_waitcnt lgkmcnt(1)
	v_pk_add_f32 v[4:5], v[4:5], v[8:9]
	s_cmpk_gt_i32 s8, 0xff
	v_pk_add_f32 v[4:5], v[4:5], v[10:11]
	s_waitcnt lgkmcnt(0)
	v_pk_add_f32 v[0:1], v[4:5], v[0:1]
	v_lshl_or_b32 v4, s12, 5, v28
	v_pk_add_f32 v[0:1], v[0:1], v[2:3]
	v_add_u32_e32 v2, s9, v27
	v_ashrrev_i32_e32 v3, 31, v2
	v_cvt_pk_bf16_f32 v6, v0, v1
	v_lshlrev_b64 v[0:1], 11, v[2:3]
	v_lshl_add_u64 v[0:1], s[10:11], 0, v[0:1]
	v_ashrrev_i32_e32 v5, 31, v4
	v_lshl_add_u64 v[0:1], v[4:5], 1, v[0:1]
	global_store_dword v[0:1], v6, off
	s_barrier
	s_cbranch_scc0 .LBB0_1067

; DI unsigned pk2(float a, float b) { f32x2 f = {a, b}; bf2_t r = __builtin_convertvector(f, bf2_t); return __builtin_bit_cast(unsigned, r); }
; DI float bf_lo(unsigned u) { return __uint_as_float(u << 16); }
; DI float bf_hi(unsigned u) { return __uint_as_float(u & 0xffff0000u); }
; DI float sigmoidf_(float x) { return __builtin_amdgcn_rcpf(1.0f + __builtin_amdgcn_exp2f(-1.4426950408889634f * x)); }
; #define MFMA32(a, b, c) __builtin_amdgcn_mfma_f32_32x32x16_bf16((a), (b), (c), 0, 0, 0)
; template <int KIND, int KSTEPS  >
; DI void gemm_small(KP P, const bf16_t* A, int lda, const bf16_t* Bt, int ldb, int N, bf16_t* C, int ldc, char* lds) {
;     ...
;             for (int s0 = 0; s0 < KSTEPS; s0 += UN) {
;                 bf16x8 af[UN], bf[UN];
; #pragma unroll
;                 for (int s = 0; s < UN; ++s) { af[s] = *(const bf16x8*)(ap + (s0 + s) * 16); bf[s] = *(const bf16x8*)(bp + (s0 + s) * 16); }
; #pragma unroll
;                 for (int s = 0; s < UN; ++s) acc = MFMA32(bf[s], af[s], acc);
;             }
;             float* pp = part + ((pass * 8 + w) * 32 + r) * 32 + 4 * hh;
; #pragma unroll
;             for (int g = 0; g < 4; ++g) *(f32x4*)(pp + 8 * g) = (f32x4){acc[4 * g], acc[4 * g + 1], acc[4 * g + 2], acc[4 * g + 3]};
;         }
;         __syncthreads();
;         {
;             const int e = tid * 2, rr = e >> 5, cc = e & 31;
;             f32x2 s1 = {0.f, 0.f}, s2 = {0.f, 0.f};
; #pragma unroll
;             for (int ww = 0; ww < 8; ++ww) { s1 += *(const f32x2*)(part + (ww * 32 + rr) * 32 + cc); if (KIND == 2) s2 += *(const f32x2*)(part + ((8 + ww) * 32 + rr) * 32 + cc); }
;             const long row = row0 + rr; const int col = col0 + cc;
;             if (KIND == 1) { s1[0] = sigmoidf_(s1[0]); s1[1] = sigmoidf_(s1[1]); }
;             if (KIND == 2) { const unsigned ga = *(const unsigned*)(P->gates + row * 2048 + col), gb = *(const unsigned*)(P->gates + row * 2048 + 1024 + col);
;                 s1[0] = s1[0] * bf_lo(ga) + s2[0] * bf_lo(gb); s1[1] = s1[1] * bf_hi(ga) + s2[1] * bf_hi(gb); }
;             *(unsigned*)(C + row * ldc + col) = pk2(s1[0], s1[1]);
;         }
;         __syncthreads();
.LBB0_1075:
	s_lshr_b32 s13, s7, 3
	s_and_b32 s12, s7, 7
	s_and_b32 s13, s13, 0x7fffff8
	s_or_b32 s12, s13, s12
	s_and_b32 s14, s8, 0xe0
	s_lshl_b32 s12, s12, 5
	s_bitset1_b32 s14, 14
	v_or_b32_e32 v4, s12, v20
	v_or_b32_e32 v0, s14, v20
	v_ashrrev_i32_e32 v5, 31, v4
	v_lshlrev_b32_e32 v140, 11, v0
	v_lshlrev_b64 v[4:5], 11, v[4:5]
	v_lshl_add_u64 v[58:59], v[16:17], 0, v[140:141]
	v_lshl_add_u64 v[60:61], v[18:19], 0, v[4:5]
	global_load_dwordx4 v[64:67], v[58:59], off
	global_load_dwordx4 v[96:99], v[60:61], off
	global_load_dwordx4 v[68:71], v[58:59], off offset:32
	global_load_dwordx4 v[100:103], v[60:61], off offset:32
	global_load_dwordx4 v[72:75], v[58:59], off offset:64
	global_load_dwordx4 v[104:107], v[60:61], off offset:64
	global_load_dwordx4 v[76:79], v[58:59], off offset:96
	global_load_dwordx4 v[108:111], v[60:61], off offset:96
	global_load_dwordx4 v[80:83], v[58:59], off offset:128
	global_load_dwordx4 v[112:115], v[60:61], off offset:128
	global_load_dwordx4 v[84:87], v[58:59], off offset:160
	global_load_dwordx4 v[116:119], v[60:61], off offset:160
	global_load_dwordx4 v[88:91], v[58:59], off offset:192
	global_load_dwordx4 v[120:123], v[60:61], off offset:192
	global_load_dwordx4 v[92:95], v[58:59], off offset:224
	global_load_dwordx4 v[124:127], v[60:61], off offset:224
	s_add_i32 s7, s7, s6
	s_add_i32 s8, s8, s9
	s_cmpk_gt_i32 s7, 0xff
	v_add_u32_e32 v38, s14, v21
	v_ashrrev_i32_e32 v39, 31, v38
	v_or_b32_e32 v30, s12, v22
	v_lshlrev_b64 v[32:33], 11, v[38:39]
	v_lshl_add_u64 v[32:33], s[10:11], 0, v[32:33]
	v_ashrrev_i32_e32 v31, 31, v30
	v_lshl_add_u64 v[30:31], v[30:31], 1, v[32:33]
	s_waitcnt vmcnt(14)
	v_mfma_f32_32x32x16_bf16 v[0:15], v[96:99], v[64:67], 0
	s_waitcnt vmcnt(12)
	v_mfma_f32_32x32x16_bf16 v[0:15], v[100:103], v[68:71], v[0:15]
	s_waitcnt vmcnt(10)
	v_mfma_f32_32x32x16_bf16 v[0:15], v[104:107], v[72:75], v[0:15]
	s_waitcnt vmcnt(8)
	v_mfma_f32_32x32x16_bf16 v[0:15], v[108:111], v[76:79], v[0:15]
	s_waitcnt vmcnt(6)
	v_mfma_f32_32x32x16_bf16 v[0:15], v[112:115], v[80:83], v[0:15]
	s_waitcnt vmcnt(4)
	v_mfma_f32_32x32x16_bf16 v[0:15], v[116:119], v[84:87], v[0:15]
	s_waitcnt vmcnt(2)
	v_mfma_f32_32x32x16_bf16 v[0:15], v[120:123], v[88:91], v[0:15]
	s_waitcnt vmcnt(0)
	v_mfma_f32_32x32x16_bf16 v[0:15], v[124:127], v[92:95], v[0:15]
	s_nop 11
	ds_write_b128 v24, v[0:3]
	ds_write_b128 v24, v[4:7] offset:32
	ds_write_b128 v24, v[8:11] offset:64
	ds_write_b128 v24, v[12:15] offset:96
	s_waitcnt lgkmcnt(0)
	s_barrier
	ds_read2st64_b64 v[0:3], v23 offset1:8
	ds_read2st64_b64 v[4:7], v23 offset0:16 offset1:24
	ds_read2st64_b64 v[8:11], v23 offset0:32 offset1:40
	ds_read2st64_b64 v[12:15], v23 offset0:48 offset1:56
	s_waitcnt lgkmcnt(3)
	v_pk_add_f32 v[0:1], v[0:1], 0 op_sel_hi:[1,0]
	s_nop 0
	v_pk_add_f32 v[0:1], v[0:1], v[2:3]
	s_waitcnt lgkmcnt(2)
	v_pk_add_f32 v[0:1], v[0:1], v[4:5]
	s_nop 0
	v_pk_add_f32 v[0:1], v[0:1], v[6:7]
	s_waitcnt lgkmcnt(1)
	v_pk_add_f32 v[0:1], v[0:1], v[8:9]
	s_nop 0
	v_pk_add_f32 v[0:1], v[0:1], v[10:11]
	s_waitcnt lgkmcnt(0)
	v_pk_add_f32 v[0:1], v[0:1], v[12:13]
	s_nop 0
	v_pk_add_f32 v[0:1], v[0:1], v[14:15]
	s_nop 0
	v_cvt_pk_bf16_f32 v0, v0, v1
	global_store_dword v[30:31], v0, off
	s_barrier
	s_cbranch_scc0 .LBB0_1075

; DI unsigned pk2(float a, float b) { f32x2 f = {a, b}; bf2_t r = __builtin_convertvector(f, bf2_t); return __builtin_bit_cast(unsigned, r); }
; DI float bf_lo(unsigned u) { return __uint_as_float(u << 16); }
; DI float bf_hi(unsigned u) { return __uint_as_float(u & 0xffff0000u); }
; DI float sigmoidf_(float x) { return __builtin_amdgcn_rcpf(1.0f + __builtin_amdgcn_exp2f(-1.4426950408889634f * x)); }
; #define MFMA32(a, b, c) __builtin_amdgcn_mfma_f32_32x32x16_bf16((a), (b), (c), 0, 0, 0)
; template <int KIND, int KSTEPS  >
; DI void gemm_small(KP P, const bf16_t* A, int lda, const bf16_t* Bt, int ldb, int N, bf16_t* C, int ldc, char* lds) {
;     ...
;             for (int s0 = 0; s0 < KSTEPS; s0 += UN) {
;                 bf16x8 af[UN], bf[UN];
; #pragma unroll
;                 for (int s = 0; s < UN; ++s) { af[s] = *(const bf16x8*)(ap + (s0 + s) * 16); bf[s] = *(const bf16x8*)(bp + (s0 + s) * 16); }
; #pragma unroll
;                 for (int s = 0; s < UN; ++s) acc = MFMA32(bf[s], af[s], acc);
;             }
;             float* pp = part + ((pass * 8 + w) * 32 + r) * 32 + 4 * hh;
; #pragma unroll
;             for (int g = 0; g < 4; ++g) *(f32x4*)(pp + 8 * g) = (f32x4){acc[4 * g], acc[4 * g + 1], acc[4 * g + 2], acc[4 * g + 3]};
;         }
;         __syncthreads();
;         {
;             const int e = tid * 2, rr = e >> 5, cc = e & 31;
;             f32x2 s1 = {0.f, 0.f}, s2 = {0.f, 0.f};
; #pragma unroll
;             for (int ww = 0; ww < 8; ++ww) { s1 += *(const f32x2*)(part + (ww * 32 + rr) * 32 + cc); if (KIND == 2) s2 += *(const f32x2*)(part + ((8 + ww) * 32 + rr) * 32 + cc); }
;             const long row = row0 + rr; const int col = col0 + cc;
;             if (KIND == 1) { s1[0] = sigmoidf_(s1[0]); s1[1] = sigmoidf_(s1[1]); }
;             if (KIND == 2) { const unsigned ga = *(const unsigned*)(P->gates + row * 2048 + col), gb = *(const unsigned*)(P->gates + row * 2048 + 1024 + col);
;                 s1[0] = s1[0] * bf_lo(ga) + s2[0] * bf_lo(gb); s1[1] = s1[1] * bf_hi(ga) + s2[1] * bf_hi(gb); }
;             *(unsigned*)(C + row * ldc + col) = pk2(s1[0], s1[1]);
;         }
;         __syncthreads();
.LBB0_1087:
	s_lshr_b32 s11, s9, 3
	s_and_b32 s10, s9, 7
	s_and_b32 s11, s11, 0x7fffff8
	s_or_b32 s10, s11, s10
	s_and_b32 s12, s2, 0xe0
	s_lshl_b32 s10, s10, 5
	s_bitset1_b32 s12, 14
	v_or_b32_e32 v4, s10, v20
	v_or_b32_e32 v0, s12, v20
	v_ashrrev_i32_e32 v5, 31, v4
	v_lshlrev_b32_e32 v140, 11, v0
	v_lshlrev_b64 v[4:5], 11, v[4:5]
	v_lshl_add_u64 v[58:59], v[16:17], 0, v[140:141]
	v_lshl_add_u64 v[60:61], v[18:19], 0, v[4:5]
	global_load_dwordx4 v[64:67], v[58:59], off
	global_load_dwordx4 v[96:99], v[60:61], off
	global_load_dwordx4 v[68:71], v[58:59], off offset:32
	global_load_dwordx4 v[100:103], v[60:61], off offset:32
	global_load_dwordx4 v[72:75], v[58:59], off offset:64
	global_load_dwordx4 v[104:107], v[60:61], off offset:64
	global_load_dwordx4 v[76:79], v[58:59], off offset:96
	global_load_dwordx4 v[108:111], v[60:61], off offset:96
	global_load_dwordx4 v[80:83], v[58:59], off offset:128
	global_load_dwordx4 v[112:115], v[60:61], off offset:128
	global_load_dwordx4 v[84:87], v[58:59], off offset:160
	global_load_dwordx4 v[116:119], v[60:61], off offset:160
	global_load_dwordx4 v[88:91], v[58:59], off offset:192
	global_load_dwordx4 v[120:123], v[60:61], off offset:192
	global_load_dwordx4 v[92:95], v[58:59], off offset:224
	global_load_dwordx4 v[124:127], v[60:61], off offset:224
	s_add_i32 s9, s9, s8
	s_add_i32 s2, s2, s3
	s_cmpk_gt_i32 s9, 0x1ff
	v_add_u32_e32 v38, s12, v21
	v_ashrrev_i32_e32 v39, 31, v38
	v_or_b32_e32 v30, s10, v22
	v_lshlrev_b64 v[32:33], 12, v[38:39]
	v_lshl_add_u64 v[32:33], s[6:7], 0, v[32:33]
	v_ashrrev_i32_e32 v31, 31, v30
	v_lshl_add_u64 v[30:31], v[30:31], 1, v[32:33]
	s_waitcnt vmcnt(14)
	v_mfma_f32_32x32x16_bf16 v[0:15], v[96:99], v[64:67], 0
	s_waitcnt vmcnt(12)
	v_mfma_f32_32x32x16_bf16 v[0:15], v[100:103], v[68:71], v[0:15]
	s_waitcnt vmcnt(10)
	v_mfma_f32_32x32x16_bf16 v[0:15], v[104:107], v[72:75], v[0:15]
	s_waitcnt vmcnt(8)
	v_mfma_f32_32x32x16_bf16 v[0:15], v[108:111], v[76:79], v[0:15]
	s_waitcnt vmcnt(6)
	v_mfma_f32_32x32x16_bf16 v[0:15], v[112:115], v[80:83], v[0:15]
	s_waitcnt vmcnt(4)
	v_mfma_f32_32x32x16_bf16 v[0:15], v[116:119], v[84:87], v[0:15]
	s_waitcnt vmcnt(2)
	v_mfma_f32_32x32x16_bf16 v[0:15], v[120:123], v[88:91], v[0:15]
	s_waitcnt vmcnt(0)
	v_mfma_f32_32x32x16_bf16 v[0:15], v[124:127], v[92:95], v[0:15]
	s_nop 11
	ds_write_b128 v24, v[0:3]
	ds_write_b128 v24, v[4:7] offset:32
	ds_write_b128 v24, v[8:11] offset:64
	ds_write_b128 v24, v[12:15] offset:96
	s_waitcnt lgkmcnt(0)
	s_barrier
	ds_read2st64_b64 v[0:3], v23 offset1:8
	ds_read2st64_b64 v[4:7], v23 offset0:16 offset1:24
	ds_read2st64_b64 v[8:11], v23 offset0:32 offset1:40
	ds_read2st64_b64 v[12:15], v23 offset0:48 offset1:56
	s_waitcnt lgkmcnt(3)
	v_pk_add_f32 v[0:1], v[0:1], 0 op_sel_hi:[1,0]
	s_nop 0
	v_pk_add_f32 v[0:1], v[0:1], v[2:3]
	s_waitcnt lgkmcnt(2)
	v_pk_add_f32 v[0:1], v[0:1], v[4:5]
	s_nop 0
	v_pk_add_f32 v[0:1], v[0:1], v[6:7]
	s_waitcnt lgkmcnt(1)
	v_pk_add_f32 v[0:1], v[0:1], v[8:9]
	s_nop 0
	v_pk_add_f32 v[0:1], v[0:1], v[10:11]
	s_waitcnt lgkmcnt(0)
	v_pk_add_f32 v[0:1], v[0:1], v[12:13]
	s_nop 0
	v_pk_add_f32 v[0:1], v[0:1], v[14:15]
	s_nop 0
	v_mul_f32_e32 v0, 0xbfb8aa3b, v0
	v_mul_f32_e32 v1, 0xbfb8aa3b, v1
	v_exp_f32_e32 v0, v0
	v_exp_f32_e32 v1, v1
	v_add_f32_e32 v0, 1.0, v0
	v_add_f32_e32 v1, 1.0, v1
	v_rcp_f32_e32 v0, v0
	v_rcp_f32_e32 v1, v1
	s_nop 0
	v_cvt_pk_bf16_f32 v0, v0, v1
	global_store_dword v[30:31], v0, off
	s_barrier
	s_cbranch_scc0 .LBB0_1087
